# SB attention: canonicalize fused into the clamp (v_min_f32 x,-z,126) and an unmasked variant of each 32-key block's sigmoid section taken when the tile lies wholly below the wave's queries
# speedup vs baseline: 1.0205x; 1.0025x over previous
.LBB0_993:
	s_or_b64 exec, exec, s[6:7]
	v_add_u32_e32 v144, 0x7f, v144
	v_add_u32_e32 v192, s86, v173
	v_cmp_lt_i32_e64 s[14:15], v144, v139
	s_mov_b64 s[6:7], 0
	s_and_saveexec_b64 s[38:39], vcc
	s_cbranch_execz .LBB0_995
	s_mov_b32 s99, 0x42fc0000
	s_cmp_eq_u64 s[14:15], exec
	s_cbranch_scc1 .Lsb_nmA
	s_nop 4
	v_min_f32_e64 v32, -v32, s99
	v_exp_f32_e32 v32, v32
	v_min_f32_e64 v33, -v33, s99
	v_exp_f32_e32 v33, v33
	v_add_f32_e32 v144, 1.0, v32
	v_rcp_f32_e32 v145, v144
	v_add_u32_e32 v144, 0x60, v192
	v_cmp_lt_i32_e64 s[18:19], v144, v187
	v_add_f32_e32 v144, 1.0, v33
	v_rcp_f32_e32 v146, v144
	v_mul_f32_e32 v32, v32, v145
	s_or_b64 s[18:19], s[14:15], s[18:19]
	v_cndmask_b32_e64 v144, 1.0, v32, s[18:19]
	v_mul_f32_e32 v32, v33, v146
	v_add_u32_e32 v33, 0x61, v192
	v_cndmask_b32_e64 v193, 0, v145, s[18:19]
	v_cmp_lt_i32_e64 s[18:19], v33, v187
	v_min_f32_e64 v33, -v34, s99
	v_exp_f32_e32 v33, v33
	v_min_f32_e64 v35, -v35, s99
	v_exp_f32_e32 v35, v35
	v_add_f32_e32 v34, 1.0, v33
	v_rcp_f32_e32 v34, v34
	s_or_b64 s[18:19], s[14:15], s[18:19]
	v_add_u32_e32 v145, 0x62, v192
	v_cndmask_b32_e64 v32, 1.0, v32, s[18:19]
	v_cndmask_b32_e64 v194, 0, v146, s[18:19]
	v_cmp_lt_i32_e64 s[18:19], v145, v187
	v_add_f32_e32 v145, 1.0, v35
	v_rcp_f32_e32 v145, v145
	s_or_b64 s[18:19], s[14:15], s[18:19]
	v_mul_f32_e32 v33, v33, v34
	v_cndmask_b32_e64 v195, 0, v34, s[18:19]
	v_add_u32_e32 v34, 0x63, v192
	v_cndmask_b32_e64 v146, 1.0, v33, s[18:19]
	v_cmp_lt_i32_e64 s[18:19], v34, v187
	v_min_f32_e64 v34, -v36, s99
	v_min_f32_e64 v36, -v37, s99
	v_mul_f32_e32 v33, v35, v145
	v_exp_f32_e32 v35, v34
	v_exp_f32_e32 v36, v36
	s_or_b64 s[18:19], s[14:15], s[18:19]
	v_add_u32_e32 v37, 0x68, v192
	v_cndmask_b32_e64 v34, 1.0, v33, s[18:19]
	v_cndmask_b32_e64 v196, 0, v145, s[18:19]
	v_add_f32_e32 v33, 1.0, v35
	v_cmp_lt_i32_e64 s[18:19], v37, v187
	v_add_f32_e32 v37, 1.0, v36
	v_rcp_f32_e32 v33, v33
	v_rcp_f32_e32 v37, v37
	s_or_b64 s[18:19], s[14:15], s[18:19]
	v_mul_f32_e32 v35, v35, v33
	v_cndmask_b32_e64 v197, 0, v33, s[18:19]
	v_mul_f32_e32 v33, v36, v37
	v_add_u32_e32 v36, 0x69, v192
	v_cndmask_b32_e64 v35, 1.0, v35, s[18:19]
	v_cmp_lt_i32_e64 s[18:19], v36, v187
	v_min_f32_e64 v36, -v38, s99
	s_or_b64 s[18:19], s[14:15], s[18:19]
	v_exp_f32_e32 v36, v36
	v_cndmask_b32_e64 v199, 0, v37, s[18:19]
	v_min_f32_e64 v37, -v39, s99
	v_exp_f32_e32 v37, v37
	v_cndmask_b32_e64 v198, 1.0, v33, s[18:19]
	v_add_f32_e32 v33, 1.0, v36
	v_rcp_f32_e32 v33, v33
	v_add_u32_e32 v38, 0x6a, v192
	v_cmp_lt_i32_e64 s[18:19], v38, v187
	v_add_f32_e32 v38, 1.0, v37
	v_rcp_f32_e32 v38, v38
	v_mul_f32_e32 v36, v36, v33
	s_or_b64 s[18:19], s[14:15], s[18:19]
	v_cndmask_b32_e64 v200, 1.0, v36, s[18:19]
	v_add_u32_e32 v36, 0x6b, v192
	v_cndmask_b32_e64 v201, 0, v33, s[18:19]
	v_mul_f32_e32 v33, v37, v38
	v_cmp_lt_i32_e64 s[18:19], v36, v187
	v_min_f32_e64 v36, -v40, s99
	v_min_f32_e64 v37, -v41, s99
	v_exp_f32_e32 v36, v36
	v_exp_f32_e32 v37, v37
	s_or_b64 s[18:19], s[14:15], s[18:19]
	v_cndmask_b32_e64 v203, 0, v38, s[18:19]
	v_add_u32_e32 v38, 0x70, v192
	v_cndmask_b32_e64 v202, 1.0, v33, s[18:19]
	v_add_f32_e32 v33, 1.0, v36
	v_cmp_lt_i32_e64 s[18:19], v38, v187
	v_add_f32_e32 v38, 1.0, v37
	v_rcp_f32_e32 v33, v33
	v_rcp_f32_e32 v38, v38
	s_or_b64 s[18:19], s[14:15], s[18:19]
	v_min_f32_e64 v41, -v43, s99
	v_mul_f32_e32 v36, v36, v33
	v_cndmask_b32_e64 v39, 0, v33, s[18:19]
	v_mul_f32_e32 v33, v37, v38
	v_add_u32_e32 v37, 0x71, v192
	v_cndmask_b32_e64 v36, 1.0, v36, s[18:19]
	v_cmp_lt_i32_e64 s[18:19], v37, v187
	v_min_f32_e64 v37, -v42, s99
	v_exp_f32_e32 v37, v37
	v_exp_f32_e32 v41, v41
	s_or_b64 s[18:19], s[14:15], s[18:19]
	v_add_u32_e32 v42, 0x72, v192
	v_cndmask_b32_e64 v40, 1.0, v33, s[18:19]
	v_cndmask_b32_e64 v38, 0, v38, s[18:19]
	v_add_f32_e32 v33, 1.0, v37
	v_cmp_lt_i32_e64 s[18:19], v42, v187
	v_add_f32_e32 v42, 1.0, v41
	v_rcp_f32_e32 v33, v33
	v_rcp_f32_e32 v42, v42
	s_or_b64 s[18:19], s[14:15], s[18:19]
	v_min_f32_e64 v43, -v45, s99
	v_mul_f32_e32 v37, v37, v33
	v_cndmask_b32_e64 v204, 0, v33, s[18:19]
	v_mul_f32_e32 v33, v41, v42
	v_add_u32_e32 v41, 0x73, v192
	v_cndmask_b32_e64 v37, 1.0, v37, s[18:19]
	v_cmp_lt_i32_e64 s[18:19], v41, v187
	v_min_f32_e64 v41, -v44, s99
	v_exp_f32_e32 v41, v41
	v_exp_f32_e32 v43, v43
	s_or_b64 s[18:19], s[14:15], s[18:19]
	v_add_u32_e32 v44, 0x78, v192
	v_cndmask_b32_e64 v205, 1.0, v33, s[18:19]
	v_cndmask_b32_e64 v42, 0, v42, s[18:19]
	v_add_f32_e32 v33, 1.0, v41
	v_cmp_lt_i32_e64 s[18:19], v44, v187
	v_add_f32_e32 v44, 1.0, v43
	v_rcp_f32_e32 v33, v33
	v_rcp_f32_e32 v44, v44
	s_or_b64 s[18:19], s[14:15], s[18:19]
	v_min_f32_e64 v45, -v47, s99
	v_mul_f32_e32 v41, v41, v33
	v_cndmask_b32_e64 v206, 0, v33, s[18:19]
	v_mul_f32_e32 v33, v43, v44
	v_add_u32_e32 v43, 0x79, v192
	v_cndmask_b32_e64 v41, 1.0, v41, s[18:19]
	v_cmp_lt_i32_e64 s[18:19], v43, v187
	v_min_f32_e64 v43, -v46, s99
	v_exp_f32_e32 v43, v43
	v_exp_f32_e32 v45, v45
	s_or_b64 s[18:19], s[14:15], s[18:19]
	v_add_u32_e32 v46, 0x7a, v192
	v_cndmask_b32_e64 v207, 1.0, v33, s[18:19]
	v_cndmask_b32_e64 v44, 0, v44, s[18:19]
	v_add_f32_e32 v33, 1.0, v43
	v_cmp_lt_i32_e64 s[18:19], v46, v187
	v_add_f32_e32 v46, 1.0, v45
	v_rcp_f32_e32 v33, v33
	v_rcp_f32_e32 v46, v46
	s_or_b64 s[18:19], s[14:15], s[18:19]
	v_and_b32_e32 v47, 64, v172
	v_mul_f32_e32 v43, v43, v33
	v_cndmask_b32_e64 v208, 0, v33, s[18:19]
	v_mul_f32_e32 v33, v45, v46
	v_add_u32_e32 v45, 0x7b, v192
	v_cndmask_b32_e64 v43, 1.0, v43, s[18:19]
	v_cmp_lt_i32_e64 s[18:19], v45, v187
	s_or_b64 s[18:19], s[14:15], s[18:19]
	v_add_u32_e32 v47, 64, v47
	v_cndmask_b32_e64 v45, 1.0, v33, s[18:19]
	v_xor_b32_e32 v33, 32, v172
	v_cndmask_b32_e64 v46, 0, v46, s[18:19]
	v_cmp_lt_i32_e64 s[18:19], v33, v47
	v_mul_f32_e32 v36, v36, v40
	v_mul_f32_e32 v47, v37, v205
	v_cndmask_b32_e64 v33, v172, v33, s[18:19]
	v_lshlrev_b32_e32 v209, 2, v33
	v_mul_f32_e32 v33, v35, v198
	v_mul_f32_e32 v35, v200, v202
	v_mul_f32_e32 v145, v33, v35
	v_mul_f32_e32 v35, v41, v207
	v_mul_f32_e32 v41, v43, v45
	v_mul_f32_e32 v35, v35, v41
.Lsb_joinA:
	ds_bpermute_b32 v41, v209, v35
	v_mul_f32_e32 v36, v36, v47
	ds_bpermute_b32 v210, v209, v36
	ds_bpermute_b32 v33, v209, v145
	s_waitcnt lgkmcnt(2)
	v_mul_f32_e32 v47, v147, v41
	v_cndmask_b32_e64 v211, v147, v47, s[10:11]
	v_mul_f32_e32 v35, v35, v41
	v_mul_f32_e32 v45, v45, v211
	v_mul_f32_e32 v35, v147, v35
	v_mul_f32_e32 v43, v43, v45
	s_waitcnt lgkmcnt(1)
	v_mul_f32_e32 v41, v35, v210
	v_mul_f32_e32 v47, v46, v211
	v_mul_f32_e32 v46, v208, v45
	v_mul_f32_e32 v45, v44, v43
	v_mul_f32_e32 v43, v207, v43
	v_cndmask_b32_e64 v41, v35, v41, s[10:11]
	v_mul_f32_e32 v44, v206, v43
	v_mul_f32_e32 v43, v42, v41
	v_mul_f32_e32 v41, v205, v41
	v_mul_f32_e32 v37, v37, v41
	v_mul_f32_e32 v42, v204, v41
	v_mul_f32_e32 v41, v38, v37
	v_mul_f32_e32 v37, v40, v37
	v_mul_f32_e32 v147, v36, v210
	v_mul_f32_e32 v40, v39, v37
	v_pk_mul_f32 v[36:37], v[146:147], v[34:35]
	s_waitcnt lgkmcnt(0)
	v_pk_mul_f32 v[38:39], v[144:145], v[32:33]
	v_mul_f32_e32 v33, v37, v33
	v_pk_mul_f32 v[144:145], v[38:39], v[36:37]
	ds_bpermute_b32 v147, v209, v144
	v_cndmask_b32_e64 v33, v37, v33, s[10:11]
	v_mul_f32_e32 v39, v203, v33
	v_mul_f32_e32 v33, v202, v33
	v_mul_f32_e32 v38, v201, v33
	v_mul_f32_e32 v33, v200, v33
	v_mul_f32_e32 v37, v199, v33
	v_mul_f32_e32 v33, v198, v33
	v_mul_f32_e32 v36, v197, v33
	s_waitcnt lgkmcnt(0)
	v_mul_f32_e32 v33, v145, v147
	v_mul_f32_e32 v144, v144, v147
	v_cndmask_b32_e64 v33, v145, v33, s[10:11]
	v_mul_f32_e32 v147, v144, v145
	v_mul_f32_e32 v35, v196, v33
	v_mul_f32_e32 v33, v34, v33
	v_cmp_gt_f32_e64 s[18:19], s81, v147
	v_mul_f32_e32 v146, v146, v33
	s_cmp_eq_u64 s[18:19], exec
	v_mul_f32_e32 v32, v32, v146
	s_cselect_b64 s[6:7], -1, 0
	v_mul_f32_e32 v34, v195, v33
	v_mul_f32_e32 v33, v194, v146
	v_mul_f32_e32 v32, v193, v32
	s_and_b64 s[6:7], s[6:7], exec

.LBB0_1002:
	s_mov_b32 s99, 0x42fc0000
	s_cmp_eq_u64 s[14:15], exec
	s_cbranch_scc1 .Lsb_nmB
	v_min_f32_e64 v48, -v48, s99
	v_exp_f32_e32 v48, v48
	v_min_f32_e64 v49, -v49, s99
	v_exp_f32_e32 v49, v49
	v_add_f32_e32 v144, 1.0, v48
	v_rcp_f32_e32 v145, v144
	v_add_u32_e32 v144, 64, v192
	v_cmp_lt_i32_e64 s[18:19], v144, v187
	v_add_f32_e32 v144, 1.0, v49
	v_rcp_f32_e32 v146, v144
	v_mul_f32_e32 v48, v48, v145
	s_or_b64 s[18:19], s[14:15], s[18:19]
	v_cndmask_b32_e64 v144, 1.0, v48, s[18:19]
	v_mul_f32_e32 v48, v49, v146
	v_add_u32_e32 v49, 0x41, v192
	v_cndmask_b32_e64 v193, 0, v145, s[18:19]
	v_cmp_lt_i32_e64 s[18:19], v49, v187
	v_min_f32_e64 v49, -v50, s99
	v_exp_f32_e32 v49, v49
	v_min_f32_e64 v51, -v51, s99
	v_exp_f32_e32 v51, v51
	v_add_f32_e32 v50, 1.0, v49
	v_rcp_f32_e32 v50, v50
	s_or_b64 s[18:19], s[14:15], s[18:19]
	v_add_u32_e32 v145, 0x42, v192
	v_cndmask_b32_e64 v48, 1.0, v48, s[18:19]
	v_cndmask_b32_e64 v194, 0, v146, s[18:19]
	v_cmp_lt_i32_e64 s[18:19], v145, v187
	v_add_f32_e32 v145, 1.0, v51
	v_rcp_f32_e32 v145, v145
	s_or_b64 s[18:19], s[14:15], s[18:19]
	v_mul_f32_e32 v49, v49, v50
	v_cndmask_b32_e64 v195, 0, v50, s[18:19]
	v_add_u32_e32 v50, 0x43, v192
	v_cndmask_b32_e64 v146, 1.0, v49, s[18:19]
	v_cmp_lt_i32_e64 s[18:19], v50, v187
	v_min_f32_e64 v50, -v52, s99
	v_min_f32_e64 v52, -v53, s99
	v_mul_f32_e32 v49, v51, v145
	v_exp_f32_e32 v51, v50
	v_exp_f32_e32 v52, v52
	s_or_b64 s[18:19], s[14:15], s[18:19]
	v_add_u32_e32 v53, 0x48, v192
	v_cndmask_b32_e64 v50, 1.0, v49, s[18:19]
	v_cndmask_b32_e64 v196, 0, v145, s[18:19]
	v_add_f32_e32 v49, 1.0, v51
	v_cmp_lt_i32_e64 s[18:19], v53, v187
	v_add_f32_e32 v53, 1.0, v52
	v_rcp_f32_e32 v49, v49
	v_rcp_f32_e32 v53, v53
	s_or_b64 s[18:19], s[14:15], s[18:19]
	v_mul_f32_e32 v51, v51, v49
	v_cndmask_b32_e64 v197, 0, v49, s[18:19]
	v_mul_f32_e32 v49, v52, v53
	v_add_u32_e32 v52, 0x49, v192
	v_cndmask_b32_e64 v51, 1.0, v51, s[18:19]
	v_cmp_lt_i32_e64 s[18:19], v52, v187
	v_min_f32_e64 v52, -v54, s99
	s_or_b64 s[18:19], s[14:15], s[18:19]
	v_exp_f32_e32 v52, v52
	v_cndmask_b32_e64 v199, 0, v53, s[18:19]
	v_min_f32_e64 v53, -v55, s99
	v_exp_f32_e32 v53, v53
	v_cndmask_b32_e64 v198, 1.0, v49, s[18:19]
	v_add_f32_e32 v49, 1.0, v52
	v_rcp_f32_e32 v49, v49
	v_add_u32_e32 v54, 0x4a, v192
	v_cmp_lt_i32_e64 s[18:19], v54, v187
	v_add_f32_e32 v54, 1.0, v53
	v_rcp_f32_e32 v54, v54
	v_mul_f32_e32 v52, v52, v49
	s_or_b64 s[18:19], s[14:15], s[18:19]
	v_cndmask_b32_e64 v200, 1.0, v52, s[18:19]
	v_add_u32_e32 v52, 0x4b, v192
	v_cndmask_b32_e64 v201, 0, v49, s[18:19]
	v_mul_f32_e32 v49, v53, v54
	v_cmp_lt_i32_e64 s[18:19], v52, v187
	v_min_f32_e64 v52, -v56, s99
	v_min_f32_e64 v53, -v57, s99
	v_exp_f32_e32 v52, v52
	v_exp_f32_e32 v53, v53
	s_or_b64 s[18:19], s[14:15], s[18:19]
	v_cndmask_b32_e64 v203, 0, v54, s[18:19]
	v_add_u32_e32 v54, 0x50, v192
	v_cndmask_b32_e64 v202, 1.0, v49, s[18:19]
	v_add_f32_e32 v49, 1.0, v52
	v_cmp_lt_i32_e64 s[18:19], v54, v187
	v_add_f32_e32 v54, 1.0, v53
	v_rcp_f32_e32 v49, v49
	v_rcp_f32_e32 v54, v54
	s_or_b64 s[18:19], s[14:15], s[18:19]
	v_min_f32_e64 v57, -v59, s99
	v_mul_f32_e32 v52, v52, v49
	v_cndmask_b32_e64 v55, 0, v49, s[18:19]
	v_mul_f32_e32 v49, v53, v54
	v_add_u32_e32 v53, 0x51, v192
	v_cndmask_b32_e64 v52, 1.0, v52, s[18:19]
	v_cmp_lt_i32_e64 s[18:19], v53, v187
	v_min_f32_e64 v53, -v58, s99
	v_exp_f32_e32 v53, v53
	v_exp_f32_e32 v57, v57
	s_or_b64 s[18:19], s[14:15], s[18:19]
	v_add_u32_e32 v58, 0x52, v192
	v_cndmask_b32_e64 v56, 1.0, v49, s[18:19]
	v_cndmask_b32_e64 v54, 0, v54, s[18:19]
	v_add_f32_e32 v49, 1.0, v53
	v_cmp_lt_i32_e64 s[18:19], v58, v187
	v_add_f32_e32 v58, 1.0, v57
	v_rcp_f32_e32 v49, v49
	v_rcp_f32_e32 v58, v58
	s_or_b64 s[18:19], s[14:15], s[18:19]
	v_min_f32_e64 v59, -v61, s99
	v_mul_f32_e32 v53, v53, v49
	v_cndmask_b32_e64 v204, 0, v49, s[18:19]
	v_mul_f32_e32 v49, v57, v58
	v_add_u32_e32 v57, 0x53, v192
	v_cndmask_b32_e64 v53, 1.0, v53, s[18:19]
	v_cmp_lt_i32_e64 s[18:19], v57, v187
	v_min_f32_e64 v57, -v60, s99
	v_exp_f32_e32 v57, v57
	v_exp_f32_e32 v59, v59
	s_or_b64 s[18:19], s[14:15], s[18:19]
	v_add_u32_e32 v60, 0x58, v192
	v_cndmask_b32_e64 v205, 1.0, v49, s[18:19]
	v_cndmask_b32_e64 v58, 0, v58, s[18:19]
	v_add_f32_e32 v49, 1.0, v57
	v_cmp_lt_i32_e64 s[18:19], v60, v187
	v_add_f32_e32 v60, 1.0, v59
	v_rcp_f32_e32 v49, v49
	v_rcp_f32_e32 v60, v60
	s_or_b64 s[18:19], s[14:15], s[18:19]
	v_min_f32_e64 v61, -v63, s99
	v_mul_f32_e32 v57, v57, v49
	v_cndmask_b32_e64 v206, 0, v49, s[18:19]
	v_mul_f32_e32 v49, v59, v60
	v_add_u32_e32 v59, 0x59, v192
	v_cndmask_b32_e64 v57, 1.0, v57, s[18:19]
	v_cmp_lt_i32_e64 s[18:19], v59, v187
	v_min_f32_e64 v59, -v62, s99
	v_exp_f32_e32 v59, v59
	v_exp_f32_e32 v61, v61
	s_or_b64 s[18:19], s[14:15], s[18:19]
	v_add_u32_e32 v62, 0x5a, v192
	v_cndmask_b32_e64 v207, 1.0, v49, s[18:19]
	v_cndmask_b32_e64 v60, 0, v60, s[18:19]
	v_add_f32_e32 v49, 1.0, v59
	v_cmp_lt_i32_e64 s[18:19], v62, v187
	v_add_f32_e32 v62, 1.0, v61
	v_rcp_f32_e32 v49, v49
	v_rcp_f32_e32 v62, v62
	s_or_b64 s[18:19], s[14:15], s[18:19]
	v_and_b32_e32 v63, 64, v172
	v_mul_f32_e32 v59, v59, v49
	v_cndmask_b32_e64 v208, 0, v49, s[18:19]
	v_mul_f32_e32 v49, v61, v62
	v_add_u32_e32 v61, 0x5b, v192
	v_cndmask_b32_e64 v59, 1.0, v59, s[18:19]
	v_cmp_lt_i32_e64 s[18:19], v61, v187
	s_or_b64 s[14:15], s[14:15], s[18:19]
	v_cndmask_b32_e64 v61, 1.0, v49, s[14:15]
	v_xor_b32_e32 v49, 32, v172
	v_add_u32_e32 v63, 64, v63
	v_cndmask_b32_e64 v62, 0, v62, s[14:15]
	v_cmp_lt_i32_e64 s[14:15], v49, v63
	v_mul_f32_e32 v52, v52, v56
	v_mul_f32_e32 v63, v53, v205
	v_cndmask_b32_e64 v49, v172, v49, s[14:15]
	v_lshlrev_b32_e32 v192, 2, v49
	v_mul_f32_e32 v49, v51, v198
	v_mul_f32_e32 v51, v200, v202
	v_mul_f32_e32 v145, v49, v51
	v_mul_f32_e32 v51, v57, v207
	v_mul_f32_e32 v57, v59, v61
	v_mul_f32_e32 v51, v51, v57
.Lsb_joinB:
	ds_bpermute_b32 v57, v192, v51
	v_mul_f32_e32 v52, v52, v63
	ds_bpermute_b32 v209, v192, v52
	ds_bpermute_b32 v49, v192, v145
	s_waitcnt lgkmcnt(2)
	v_mul_f32_e32 v63, v147, v57
	v_cndmask_b32_e64 v210, v147, v63, s[10:11]
	v_mul_f32_e32 v51, v51, v57
	v_mul_f32_e32 v61, v61, v210
	v_mul_f32_e32 v51, v147, v51
	v_mul_f32_e32 v59, v59, v61
	s_waitcnt lgkmcnt(1)
	v_mul_f32_e32 v57, v51, v209
	v_mul_f32_e32 v63, v62, v210
	v_mul_f32_e32 v62, v208, v61
	v_mul_f32_e32 v61, v60, v59
	v_mul_f32_e32 v59, v207, v59
	v_cndmask_b32_e64 v57, v51, v57, s[10:11]
	v_mul_f32_e32 v60, v206, v59
	v_mul_f32_e32 v59, v58, v57
	v_mul_f32_e32 v57, v205, v57
	v_mul_f32_e32 v53, v53, v57
	v_mul_f32_e32 v58, v204, v57
	v_mul_f32_e32 v57, v54, v53
	v_mul_f32_e32 v53, v56, v53
	v_mul_f32_e32 v147, v52, v209
	v_mul_f32_e32 v56, v55, v53
	v_pk_mul_f32 v[52:53], v[146:147], v[50:51]
	s_waitcnt lgkmcnt(0)
	v_pk_mul_f32 v[54:55], v[144:145], v[48:49]
	v_mul_f32_e32 v49, v53, v49
	v_pk_mul_f32 v[144:145], v[54:55], v[52:53]
	ds_bpermute_b32 v147, v192, v144
	v_cndmask_b32_e64 v49, v53, v49, s[10:11]
	v_mul_f32_e32 v55, v203, v49
	v_mul_f32_e32 v49, v202, v49
	v_mul_f32_e32 v54, v201, v49
	v_mul_f32_e32 v49, v200, v49
	v_mul_f32_e32 v53, v199, v49
	v_mul_f32_e32 v49, v198, v49
	v_mul_f32_e32 v52, v197, v49
	s_waitcnt lgkmcnt(0)
	v_mul_f32_e32 v49, v145, v147
	v_mul_f32_e32 v144, v144, v147
	v_cndmask_b32_e64 v49, v145, v49, s[10:11]
	v_mul_f32_e32 v147, v144, v145
	v_mul_f32_e32 v51, v196, v49
	v_mul_f32_e32 v49, v50, v49
	v_cmp_gt_f32_e64 s[14:15], s81, v147
	v_mul_f32_e32 v146, v146, v49
	s_cmp_eq_u64 s[14:15], exec
	v_mul_f32_e32 v48, v48, v146
	s_cselect_b64 s[6:7], -1, 0
	v_mul_f32_e32 v50, v195, v49
	v_mul_f32_e32 v49, v194, v146
	v_mul_f32_e32 v48, v193, v48
	s_orn2_b64 s[18:19], s[6:7], exec
	s_or_b64 exec, exec, s[40:41]
	s_and_saveexec_b64 s[14:15], s[38:39]
	s_cbranch_execz .LBB0_997

.Lsb_nmA:
	s_nop 4
	v_min_f32_e64 v32, -v32, s99
	v_exp_f32_e32 v32, v32
	v_min_f32_e64 v33, -v33, s99
	v_exp_f32_e32 v33, v33
	v_add_f32_e32 v144, 1.0, v32
	v_rcp_f32_e32 v145, v144
	v_add_f32_e32 v144, 1.0, v33
	v_rcp_f32_e32 v146, v144
	v_mul_f32_e32 v32, v32, v145
	v_mov_b32_e32 v144, v32
	v_mul_f32_e32 v32, v33, v146
	v_mov_b32_e32 v193, v145
	v_min_f32_e64 v33, -v34, s99
	v_exp_f32_e32 v33, v33
	v_min_f32_e64 v35, -v35, s99
	v_exp_f32_e32 v35, v35
	v_add_f32_e32 v34, 1.0, v33
	v_rcp_f32_e32 v34, v34
	v_mov_b32_e32 v194, v146
	v_add_f32_e32 v145, 1.0, v35
	v_rcp_f32_e32 v145, v145
	v_mul_f32_e32 v33, v33, v34
	v_mov_b32_e32 v195, v34
	v_mov_b32_e32 v146, v33
	v_min_f32_e64 v34, -v36, s99
	v_min_f32_e64 v36, -v37, s99
	v_mul_f32_e32 v33, v35, v145
	v_exp_f32_e32 v35, v34
	v_exp_f32_e32 v36, v36
	v_mov_b32_e32 v34, v33
	v_mov_b32_e32 v196, v145
	v_add_f32_e32 v33, 1.0, v35
	v_add_f32_e32 v37, 1.0, v36
	v_rcp_f32_e32 v33, v33
	v_rcp_f32_e32 v37, v37
	v_mul_f32_e32 v35, v35, v33
	v_mov_b32_e32 v197, v33
	v_mul_f32_e32 v33, v36, v37
	v_min_f32_e64 v36, -v38, s99
	v_exp_f32_e32 v36, v36
	v_mov_b32_e32 v199, v37
	v_min_f32_e64 v37, -v39, s99
	v_exp_f32_e32 v37, v37
	v_mov_b32_e32 v198, v33
	v_add_f32_e32 v33, 1.0, v36
	v_rcp_f32_e32 v33, v33
	v_add_f32_e32 v38, 1.0, v37
	v_rcp_f32_e32 v38, v38
	v_mul_f32_e32 v36, v36, v33
	v_mov_b32_e32 v200, v36
	v_mov_b32_e32 v201, v33
	v_mul_f32_e32 v33, v37, v38
	v_min_f32_e64 v36, -v40, s99
	v_min_f32_e64 v37, -v41, s99
	v_exp_f32_e32 v36, v36
	v_exp_f32_e32 v37, v37
	v_mov_b32_e32 v203, v38
	v_mov_b32_e32 v202, v33
	v_add_f32_e32 v33, 1.0, v36
	v_add_f32_e32 v38, 1.0, v37
	v_rcp_f32_e32 v33, v33
	v_rcp_f32_e32 v38, v38
	v_min_f32_e64 v41, -v43, s99
	v_mul_f32_e32 v36, v36, v33
	v_mov_b32_e32 v39, v33
	v_mul_f32_e32 v33, v37, v38
	v_min_f32_e64 v37, -v42, s99
	v_exp_f32_e32 v37, v37
	v_exp_f32_e32 v41, v41
	v_mov_b32_e32 v40, v33
	v_add_f32_e32 v33, 1.0, v37
	v_add_f32_e32 v42, 1.0, v41
	v_rcp_f32_e32 v33, v33
	v_rcp_f32_e32 v42, v42
	v_min_f32_e64 v43, -v45, s99
	v_mul_f32_e32 v37, v37, v33
	v_mov_b32_e32 v204, v33
	v_mul_f32_e32 v33, v41, v42
	v_min_f32_e64 v41, -v44, s99
	v_exp_f32_e32 v41, v41
	v_exp_f32_e32 v43, v43
	v_mov_b32_e32 v205, v33
	v_add_f32_e32 v33, 1.0, v41
	v_add_f32_e32 v44, 1.0, v43
	v_rcp_f32_e32 v33, v33
	v_rcp_f32_e32 v44, v44
	v_min_f32_e64 v45, -v47, s99
	v_mul_f32_e32 v41, v41, v33
	v_mov_b32_e32 v206, v33
	v_mul_f32_e32 v33, v43, v44
	v_min_f32_e64 v43, -v46, s99
	v_exp_f32_e32 v43, v43
	v_exp_f32_e32 v45, v45
	v_mov_b32_e32 v207, v33
	v_add_f32_e32 v33, 1.0, v43
	v_add_f32_e32 v46, 1.0, v45
	v_rcp_f32_e32 v33, v33
	v_rcp_f32_e32 v46, v46
	v_and_b32_e32 v47, 64, v172
	v_mul_f32_e32 v43, v43, v33
	v_mov_b32_e32 v208, v33
	v_mul_f32_e32 v33, v45, v46
	v_add_u32_e32 v47, 64, v47
	v_mov_b32_e32 v45, v33
	v_xor_b32_e32 v33, 32, v172
	v_cmp_lt_i32_e64 s[18:19], v33, v47
	v_mul_f32_e32 v36, v36, v40
	v_mul_f32_e32 v47, v37, v205
	v_cndmask_b32_e64 v33, v172, v33, s[18:19]
	v_lshlrev_b32_e32 v209, 2, v33
	v_mul_f32_e32 v33, v35, v198
	v_mul_f32_e32 v35, v200, v202
	v_mul_f32_e32 v145, v33, v35
	v_mul_f32_e32 v35, v41, v207
	v_mul_f32_e32 v41, v43, v45
	v_mul_f32_e32 v35, v35, v41
	s_branch .Lsb_joinA
.Lsb_nmB:
	v_min_f32_e64 v48, -v48, s99
	v_exp_f32_e32 v48, v48
	v_min_f32_e64 v49, -v49, s99
	v_exp_f32_e32 v49, v49
	v_add_f32_e32 v144, 1.0, v48
	v_rcp_f32_e32 v145, v144
	v_add_f32_e32 v144, 1.0, v49
	v_rcp_f32_e32 v146, v144
	v_mul_f32_e32 v48, v48, v145
	v_mov_b32_e32 v144, v48
	v_mul_f32_e32 v48, v49, v146
	v_mov_b32_e32 v193, v145
	v_min_f32_e64 v49, -v50, s99
	v_exp_f32_e32 v49, v49
	v_min_f32_e64 v51, -v51, s99
	v_exp_f32_e32 v51, v51
	v_add_f32_e32 v50, 1.0, v49
	v_rcp_f32_e32 v50, v50
	v_mov_b32_e32 v194, v146
	v_add_f32_e32 v145, 1.0, v51
	v_rcp_f32_e32 v145, v145
	v_mul_f32_e32 v49, v49, v50
	v_mov_b32_e32 v195, v50
	v_mov_b32_e32 v146, v49
	v_min_f32_e64 v50, -v52, s99
	v_min_f32_e64 v52, -v53, s99
	v_mul_f32_e32 v49, v51, v145
	v_exp_f32_e32 v51, v50
	v_exp_f32_e32 v52, v52
	v_mov_b32_e32 v50, v49
	v_mov_b32_e32 v196, v145
	v_add_f32_e32 v49, 1.0, v51
	v_add_f32_e32 v53, 1.0, v52
	v_rcp_f32_e32 v49, v49
	v_rcp_f32_e32 v53, v53
	v_mul_f32_e32 v51, v51, v49
	v_mov_b32_e32 v197, v49
	v_mul_f32_e32 v49, v52, v53
	v_min_f32_e64 v52, -v54, s99
	v_exp_f32_e32 v52, v52
	v_mov_b32_e32 v199, v53
	v_min_f32_e64 v53, -v55, s99
	v_exp_f32_e32 v53, v53
	v_mov_b32_e32 v198, v49
	v_add_f32_e32 v49, 1.0, v52
	v_rcp_f32_e32 v49, v49
	v_add_f32_e32 v54, 1.0, v53
	v_rcp_f32_e32 v54, v54
	v_mul_f32_e32 v52, v52, v49
	v_mov_b32_e32 v200, v52
	v_mov_b32_e32 v201, v49
	v_mul_f32_e32 v49, v53, v54
	v_min_f32_e64 v52, -v56, s99
	v_min_f32_e64 v53, -v57, s99
	v_exp_f32_e32 v52, v52
	v_exp_f32_e32 v53, v53
	v_mov_b32_e32 v203, v54
	v_mov_b32_e32 v202, v49
	v_add_f32_e32 v49, 1.0, v52
	v_add_f32_e32 v54, 1.0, v53
	v_rcp_f32_e32 v49, v49
	v_rcp_f32_e32 v54, v54
	v_min_f32_e64 v57, -v59, s99
	v_mul_f32_e32 v52, v52, v49
	v_mov_b32_e32 v55, v49
	v_mul_f32_e32 v49, v53, v54
	v_min_f32_e64 v53, -v58, s99
	v_exp_f32_e32 v53, v53
	v_exp_f32_e32 v57, v57
	v_mov_b32_e32 v56, v49
	v_add_f32_e32 v49, 1.0, v53
	v_add_f32_e32 v58, 1.0, v57
	v_rcp_f32_e32 v49, v49
	v_rcp_f32_e32 v58, v58
	v_min_f32_e64 v59, -v61, s99
	v_mul_f32_e32 v53, v53, v49
	v_mov_b32_e32 v204, v49
	v_mul_f32_e32 v49, v57, v58
	v_min_f32_e64 v57, -v60, s99
	v_exp_f32_e32 v57, v57
	v_exp_f32_e32 v59, v59
	v_mov_b32_e32 v205, v49
	v_add_f32_e32 v49, 1.0, v57
	v_add_f32_e32 v60, 1.0, v59
	v_rcp_f32_e32 v49, v49
	v_rcp_f32_e32 v60, v60
	v_min_f32_e64 v61, -v63, s99
	v_mul_f32_e32 v57, v57, v49
	v_mov_b32_e32 v206, v49
	v_mul_f32_e32 v49, v59, v60
	v_min_f32_e64 v59, -v62, s99
	v_exp_f32_e32 v59, v59
	v_exp_f32_e32 v61, v61
	v_mov_b32_e32 v207, v49
	v_add_f32_e32 v49, 1.0, v59
	v_add_f32_e32 v62, 1.0, v61
	v_rcp_f32_e32 v49, v49
	v_rcp_f32_e32 v62, v62
	v_and_b32_e32 v63, 64, v172
	v_mul_f32_e32 v59, v59, v49
	v_mov_b32_e32 v208, v49
	v_mul_f32_e32 v49, v61, v62
	v_mov_b32_e32 v61, v49
	v_xor_b32_e32 v49, 32, v172
	v_add_u32_e32 v63, 64, v63
	v_cmp_lt_i32_e64 s[14:15], v49, v63
	v_mul_f32_e32 v52, v52, v56
	v_mul_f32_e32 v63, v53, v205
	v_cndmask_b32_e64 v49, v172, v49, s[14:15]
	v_lshlrev_b32_e32 v192, 2, v49
	v_mul_f32_e32 v49, v51, v198
	v_mul_f32_e32 v51, v200, v202
	v_mul_f32_e32 v145, v49, v51
	v_mul_f32_e32 v51, v57, v207
	v_mul_f32_e32 v57, v59, v61
	v_mul_f32_e32 v51, v51, v57
	s_branch .Lsb_joinB
